# P4 SwiGLU epilogue rewritten by hand: per-row constants folded (c1=-log2e*rs, c2=rs^2), packed ops, running store address instead of a 64-bit mad per row group
# baseline (speedup 1.0000x reference)
; #define LAS __attribute__((address_space(3)))
; __device__ __forceinline__ u32x4 pack8(const f32x4 a, const f32x4 b) { u32x4 w; w.x = cvtpk(a[0], a[1]); w.y = cvtpk(a[2], a[3]); w.z = cvtpk(b[0], b[1]); w.w = cvtpk(b[2], b[3]); return w; }
;     __device__ __forceinline__ void run(const f32x4 (&acc)[2][2][4][2], const Unit& u, int wr, int wc, int fr, int fq, const int nai, LAS unsigned char* lds, const int ui) const {
;         const LAS float* RT = (const LAS float*)(lds + LDS_RSTAB) + (ui & 1) * 256;
; #pragma unroll
;         for (int ai = 0; ai < nai; ++ai)
; #pragma unroll
;             for (int m = 0; m < 4; ++m) {
;                 const int r = u.pm * 256 + ai * 128 + wr * 64 + m * 16 + fr;
;                 const float rs = RT[ai * 128 + wr * 64 + m * 16 + fr];
;                 f32x4 a[2];
; #pragma unroll
;                 for (int n = 0; n < 2; ++n) {
;                     const f32x4 g = acc[ai][0][m][n] * rs, uu = acc[ai][1][m][n] * rs;
; #pragma unroll
;                     for (int i = 0; i < 4; ++i) a[n][i] = g[i] * uu[i] * __builtin_amdgcn_rcpf(1.0f + __expf(-g[i]));
;                 }
;                 *(u32x4*)(ACT + (size_t)r * DFF + u.pn * 128 + wc * 32 + 8 * fq) = pack8(a[0], a[1]);
.LBB0_784:
	v_lshl_add_u32 v50, s59, 8, v154
	v_ashrrev_i32_e32 v51, 31, v50
	s_lshl_b32 s11, s34, 10
	v_lshlrev_b64 v[50:51], 6, v[50:51]
	s_and_b32 s11, s11, 0x400
	v_lshl_add_u64 v[54:55], v[146:147], 0, v[50:51]
	v_add_u32_e32 v162, s11, v158
	global_load_dwordx4 v[50:53], v[54:55], off
	s_nop 0
	global_load_dwordx4 v[54:57], v[54:55], off offset:16
	ds_read_b32 v163, v162
	ds_read_b32 v164, v162 offset:64
	ds_read_b32 v165, v162 offset:128
	s_lshl_b32 s46, s35, 7
	v_lshl_add_u32 v161, s58, 8, v156
	s_ashr_i32 s47, s46, 31
	s_movk_i32 s11, 0x1600
	s_lshl_b64 s[46:47], s[46:47], 1
	s_waitcnt lgkmcnt(2)
	v_mul_f32_e32 v152, 0xbfb8aa3b, v163
	v_mul_f32_e32 v153, v163, v163
	v_pk_mul_f32 v[130:131], v[134:135], v[130:131]
	v_pk_mul_f32 v[132:133], v[136:137], v[132:133]
	v_pk_mul_f32 v[122:123], v[126:127], v[122:123]
	v_pk_mul_f32 v[124:125], v[128:129], v[124:125]
	v_pk_mul_f32 v[134:135], v[134:135], v[152:153] op_sel_hi:[1,0]
	v_pk_mul_f32 v[136:137], v[136:137], v[152:153] op_sel_hi:[1,0]
	v_pk_mul_f32 v[126:127], v[126:127], v[152:153] op_sel_hi:[1,0]
	v_pk_mul_f32 v[128:129], v[128:129], v[152:153] op_sel_hi:[1,0]
	v_exp_f32_e32 v134, v134
	v_exp_f32_e32 v135, v135
	v_exp_f32_e32 v136, v136
	v_exp_f32_e32 v137, v137
	v_exp_f32_e32 v126, v126
	v_exp_f32_e32 v127, v127
	v_exp_f32_e32 v128, v128
	v_exp_f32_e32 v129, v129
	v_pk_add_f32 v[134:135], v[134:135], 1.0 op_sel_hi:[1,0]
	v_pk_add_f32 v[136:137], v[136:137], 1.0 op_sel_hi:[1,0]
	v_pk_add_f32 v[126:127], v[126:127], 1.0 op_sel_hi:[1,0]
	v_pk_add_f32 v[128:129], v[128:129], 1.0 op_sel_hi:[1,0]
	v_rcp_f32_e32 v134, v134
	v_rcp_f32_e32 v135, v135
	v_rcp_f32_e32 v136, v136
	v_rcp_f32_e32 v137, v137
	v_rcp_f32_e32 v126, v126
	v_rcp_f32_e32 v127, v127
	v_rcp_f32_e32 v128, v128
	v_rcp_f32_e32 v129, v129
	v_pk_mul_f32 v[130:131], v[130:131], v[152:153] op_sel:[0,1] op_sel_hi:[1,1]
	v_pk_mul_f32 v[132:133], v[132:133], v[152:153] op_sel:[0,1] op_sel_hi:[1,1]
	v_pk_mul_f32 v[122:123], v[122:123], v[152:153] op_sel:[0,1] op_sel_hi:[1,1]
	v_pk_mul_f32 v[124:125], v[124:125], v[152:153] op_sel:[0,1] op_sel_hi:[1,1]
	v_pk_mul_f32 v[130:131], v[130:131], v[134:135]
	v_pk_mul_f32 v[132:133], v[132:133], v[136:137]
	v_pk_mul_f32 v[122:123], v[122:123], v[126:127]
	v_pk_mul_f32 v[124:125], v[124:125], v[128:129]
	v_cvt_pk_bf16_f32 v126, v130, v131
	v_cvt_pk_bf16_f32 v127, v132, v133
	v_cvt_pk_bf16_f32 v128, v122, v123
	v_cvt_pk_bf16_f32 v129, v124, v125
	v_mov_b64_e32 v[136:137], s[16:17]
	v_mad_i64_i32 v[136:137], s[30:31], v161, s11, v[136:137]
	v_lshl_add_u64 v[136:137], v[136:137], 0, s[46:47]
	v_lshl_add_u64 v[136:137], v[136:137], 0, s[6:7]
	v_lshl_add_u64 v[136:137], v[136:137], 0, v[0:1]
	global_store_dwordx4 v[136:137], v[126:129], off
	ds_read_b32 v134, v162 offset:192
	ds_read_b32 v135, v162 offset:512
	ds_read_b32 v130, v162 offset:576
	ds_read_b32 v131, v162 offset:640
	ds_read_b32 v132, v162 offset:704
	s_waitcnt lgkmcnt(6)
	v_mul_f32_e32 v152, 0xbfb8aa3b, v164
	v_mul_f32_e32 v153, v164, v164
	v_pk_mul_f32 v[114:115], v[118:119], v[114:115]
	v_pk_mul_f32 v[116:117], v[120:121], v[116:117]
	v_pk_mul_f32 v[106:107], v[110:111], v[106:107]
	v_pk_mul_f32 v[108:109], v[112:113], v[108:109]
	v_pk_mul_f32 v[118:119], v[118:119], v[152:153] op_sel_hi:[1,0]
	v_pk_mul_f32 v[120:121], v[120:121], v[152:153] op_sel_hi:[1,0]
	v_pk_mul_f32 v[110:111], v[110:111], v[152:153] op_sel_hi:[1,0]
	v_pk_mul_f32 v[112:113], v[112:113], v[152:153] op_sel_hi:[1,0]
	v_exp_f32_e32 v118, v118
	v_exp_f32_e32 v119, v119
	v_exp_f32_e32 v120, v120
	v_exp_f32_e32 v121, v121
	v_exp_f32_e32 v110, v110
	v_exp_f32_e32 v111, v111
	v_exp_f32_e32 v112, v112
	v_exp_f32_e32 v113, v113
	v_pk_add_f32 v[118:119], v[118:119], 1.0 op_sel_hi:[1,0]
	v_pk_add_f32 v[120:121], v[120:121], 1.0 op_sel_hi:[1,0]
	v_pk_add_f32 v[110:111], v[110:111], 1.0 op_sel_hi:[1,0]
	v_pk_add_f32 v[112:113], v[112:113], 1.0 op_sel_hi:[1,0]
	v_rcp_f32_e32 v118, v118
	v_rcp_f32_e32 v119, v119
	v_rcp_f32_e32 v120, v120
	v_rcp_f32_e32 v121, v121
	v_rcp_f32_e32 v110, v110
	v_rcp_f32_e32 v111, v111
	v_rcp_f32_e32 v112, v112
	v_rcp_f32_e32 v113, v113
	v_pk_mul_f32 v[114:115], v[114:115], v[152:153] op_sel:[0,1] op_sel_hi:[1,1]
	v_pk_mul_f32 v[116:117], v[116:117], v[152:153] op_sel:[0,1] op_sel_hi:[1,1]
	v_pk_mul_f32 v[106:107], v[106:107], v[152:153] op_sel:[0,1] op_sel_hi:[1,1]
	v_pk_mul_f32 v[108:109], v[108:109], v[152:153] op_sel:[0,1] op_sel_hi:[1,1]
	v_pk_mul_f32 v[114:115], v[114:115], v[118:119]
	v_pk_mul_f32 v[116:117], v[116:117], v[120:121]
	v_pk_mul_f32 v[106:107], v[106:107], v[110:111]
	v_pk_mul_f32 v[108:109], v[108:109], v[112:113]
	v_cvt_pk_bf16_f32 v110, v114, v115
	v_cvt_pk_bf16_f32 v111, v116, v117
	v_cvt_pk_bf16_f32 v112, v106, v107
	v_cvt_pk_bf16_f32 v113, v108, v109
	s_mov_b64 s[30:31], 0x16000
	v_lshl_add_u64 v[136:137], v[136:137], 0, s[30:31]
	global_store_dwordx4 v[136:137], v[110:113], off
	s_waitcnt lgkmcnt(5)
; __device__ __forceinline__ u32x4 pack8(const f32x4 a, const f32x4 b) { u32x4 w; w.x = cvtpk(a[0], a[1]); w.y = cvtpk(a[2], a[3]); w.z = cvtpk(b[0], b[1]); w.w = cvtpk(b[2], b[3]); return w; }
;     __device__ __forceinline__ void run(const f32x4 (&acc)[2][2][4][2], const Unit& u, int wr, int wc, int fr, int fq, const int nai, LAS unsigned char* lds, const int ui) const {
;     ...
;         for (int ai = 0; ai < nai; ++ai)
; #pragma unroll
;             for (int m = 0; m < 4; ++m) {
;                 const int r = u.pm * 256 + ai * 128 + wr * 64 + m * 16 + fr;
;                 const float rs = RT[ai * 128 + wr * 64 + m * 16 + fr];
;                 f32x4 a[2];
; #pragma unroll
;                 for (int n = 0; n < 2; ++n) {
;                     const f32x4 g = acc[ai][0][m][n] * rs, uu = acc[ai][1][m][n] * rs;
; #pragma unroll
;                     for (int i = 0; i < 4; ++i) a[n][i] = g[i] * uu[i] * __builtin_amdgcn_rcpf(1.0f + __expf(-g[i]));
;                 }
;                 *(u32x4*)(ACT + (size_t)r * DFF + u.pn * 128 + wc * 32 + 8 * fq) = pack8(a[0], a[1]);
	v_mul_f32_e32 v152, 0xbfb8aa3b, v165
	v_mul_f32_e32 v153, v165, v165
	v_pk_mul_f32 v[98:99], v[102:103], v[98:99]
	v_pk_mul_f32 v[100:101], v[104:105], v[100:101]
	v_pk_mul_f32 v[90:91], v[94:95], v[90:91]
	v_pk_mul_f32 v[92:93], v[96:97], v[92:93]
	v_pk_mul_f32 v[102:103], v[102:103], v[152:153] op_sel_hi:[1,0]
	v_pk_mul_f32 v[104:105], v[104:105], v[152:153] op_sel_hi:[1,0]
	v_pk_mul_f32 v[94:95], v[94:95], v[152:153] op_sel_hi:[1,0]
	v_pk_mul_f32 v[96:97], v[96:97], v[152:153] op_sel_hi:[1,0]
	v_exp_f32_e32 v102, v102
	v_exp_f32_e32 v103, v103
	v_exp_f32_e32 v104, v104
	v_exp_f32_e32 v105, v105
	v_exp_f32_e32 v94, v94
	v_exp_f32_e32 v95, v95
	v_exp_f32_e32 v96, v96
	v_exp_f32_e32 v97, v97
	v_pk_add_f32 v[102:103], v[102:103], 1.0 op_sel_hi:[1,0]
	v_pk_add_f32 v[104:105], v[104:105], 1.0 op_sel_hi:[1,0]
	v_pk_add_f32 v[94:95], v[94:95], 1.0 op_sel_hi:[1,0]
	v_pk_add_f32 v[96:97], v[96:97], 1.0 op_sel_hi:[1,0]
	v_rcp_f32_e32 v102, v102
	v_rcp_f32_e32 v103, v103
	v_rcp_f32_e32 v104, v104
	v_rcp_f32_e32 v105, v105
	v_rcp_f32_e32 v94, v94
	v_rcp_f32_e32 v95, v95
	v_rcp_f32_e32 v96, v96
	v_rcp_f32_e32 v97, v97
	v_pk_mul_f32 v[98:99], v[98:99], v[152:153] op_sel:[0,1] op_sel_hi:[1,1]
	v_pk_mul_f32 v[100:101], v[100:101], v[152:153] op_sel:[0,1] op_sel_hi:[1,1]
	v_pk_mul_f32 v[90:91], v[90:91], v[152:153] op_sel:[0,1] op_sel_hi:[1,1]
	v_pk_mul_f32 v[92:93], v[92:93], v[152:153] op_sel:[0,1] op_sel_hi:[1,1]
	v_pk_mul_f32 v[98:99], v[98:99], v[102:103]
	v_pk_mul_f32 v[100:101], v[100:101], v[104:105]
	v_pk_mul_f32 v[90:91], v[90:91], v[94:95]
	v_pk_mul_f32 v[92:93], v[92:93], v[96:97]
	v_cvt_pk_bf16_f32 v94, v98, v99
	v_cvt_pk_bf16_f32 v95, v100, v101
	v_cvt_pk_bf16_f32 v96, v90, v91
	v_cvt_pk_bf16_f32 v97, v92, v93
	s_mov_b64 s[30:31], 0x16000
	v_lshl_add_u64 v[136:137], v[136:137], 0, s[30:31]
	global_store_dwordx4 v[136:137], v[94:97], off
	s_waitcnt lgkmcnt(4)
	v_mul_f32_e32 v152, 0xbfb8aa3b, v134
	v_mul_f32_e32 v153, v134, v134
	v_pk_mul_f32 v[82:83], v[86:87], v[82:83]
	v_pk_mul_f32 v[84:85], v[88:89], v[84:85]
	v_pk_mul_f32 v[74:75], v[78:79], v[74:75]
	v_pk_mul_f32 v[76:77], v[80:81], v[76:77]
	v_pk_mul_f32 v[86:87], v[86:87], v[152:153] op_sel_hi:[1,0]
	v_pk_mul_f32 v[88:89], v[88:89], v[152:153] op_sel_hi:[1,0]
	v_pk_mul_f32 v[78:79], v[78:79], v[152:153] op_sel_hi:[1,0]
	v_pk_mul_f32 v[80:81], v[80:81], v[152:153] op_sel_hi:[1,0]
	v_exp_f32_e32 v86, v86
	v_exp_f32_e32 v87, v87
	v_exp_f32_e32 v88, v88
	v_exp_f32_e32 v89, v89
	v_exp_f32_e32 v78, v78
	v_exp_f32_e32 v79, v79
	v_exp_f32_e32 v80, v80
	v_exp_f32_e32 v81, v81
	v_pk_add_f32 v[86:87], v[86:87], 1.0 op_sel_hi:[1,0]
	v_pk_add_f32 v[88:89], v[88:89], 1.0 op_sel_hi:[1,0]
	v_pk_add_f32 v[78:79], v[78:79], 1.0 op_sel_hi:[1,0]
	v_pk_add_f32 v[80:81], v[80:81], 1.0 op_sel_hi:[1,0]
	v_rcp_f32_e32 v86, v86
	v_rcp_f32_e32 v87, v87
	v_rcp_f32_e32 v88, v88
	v_rcp_f32_e32 v89, v89
	v_rcp_f32_e32 v78, v78
	v_rcp_f32_e32 v79, v79
	v_rcp_f32_e32 v80, v80
	v_rcp_f32_e32 v81, v81
	v_pk_mul_f32 v[82:83], v[82:83], v[152:153] op_sel:[0,1] op_sel_hi:[1,1]
	v_pk_mul_f32 v[84:85], v[84:85], v[152:153] op_sel:[0,1] op_sel_hi:[1,1]
	v_pk_mul_f32 v[74:75], v[74:75], v[152:153] op_sel:[0,1] op_sel_hi:[1,1]
	v_pk_mul_f32 v[76:77], v[76:77], v[152:153] op_sel:[0,1] op_sel_hi:[1,1]
	v_pk_mul_f32 v[82:83], v[82:83], v[86:87]
	v_pk_mul_f32 v[84:85], v[84:85], v[88:89]
	v_pk_mul_f32 v[74:75], v[74:75], v[78:79]
	v_pk_mul_f32 v[76:77], v[76:77], v[80:81]
	v_cvt_pk_bf16_f32 v78, v82, v83
	v_cvt_pk_bf16_f32 v79, v84, v85
	v_cvt_pk_bf16_f32 v80, v74, v75
	v_cvt_pk_bf16_f32 v81, v76, v77
	s_mov_b64 s[30:31], 0x16000
	v_lshl_add_u64 v[136:137], v[136:137], 0, s[30:31]
	global_store_dwordx4 v[136:137], v[78:81], off
	s_waitcnt lgkmcnt(3)
	v_mul_f32_e32 v152, 0xbfb8aa3b, v135
	v_mul_f32_e32 v153, v135, v135
	v_pk_mul_f32 v[66:67], v[70:71], v[66:67]
	v_pk_mul_f32 v[68:69], v[72:73], v[68:69]
	v_pk_mul_f32 v[58:59], v[62:63], v[58:59]
	v_pk_mul_f32 v[60:61], v[64:65], v[60:61]
	v_pk_mul_f32 v[70:71], v[70:71], v[152:153] op_sel_hi:[1,0]
	v_pk_mul_f32 v[72:73], v[72:73], v[152:153] op_sel_hi:[1,0]
	v_pk_mul_f32 v[62:63], v[62:63], v[152:153] op_sel_hi:[1,0]
	v_pk_mul_f32 v[64:65], v[64:65], v[152:153] op_sel_hi:[1,0]
	v_exp_f32_e32 v70, v70
	v_exp_f32_e32 v71, v71
	v_exp_f32_e32 v72, v72
	v_exp_f32_e32 v73, v73
	v_exp_f32_e32 v62, v62
	v_exp_f32_e32 v63, v63
	v_exp_f32_e32 v64, v64
	v_exp_f32_e32 v65, v65
	v_pk_add_f32 v[70:71], v[70:71], 1.0 op_sel_hi:[1,0]
	v_pk_add_f32 v[72:73], v[72:73], 1.0 op_sel_hi:[1,0]
	v_pk_add_f32 v[62:63], v[62:63], 1.0 op_sel_hi:[1,0]
	v_pk_add_f32 v[64:65], v[64:65], 1.0 op_sel_hi:[1,0]
	v_rcp_f32_e32 v70, v70
	v_rcp_f32_e32 v71, v71
	v_rcp_f32_e32 v72, v72
	v_rcp_f32_e32 v73, v73
	v_rcp_f32_e32 v62, v62
	v_rcp_f32_e32 v63, v63
	v_rcp_f32_e32 v64, v64
	v_rcp_f32_e32 v65, v65
	v_pk_mul_f32 v[66:67], v[66:67], v[152:153] op_sel:[0,1] op_sel_hi:[1,1]
	v_pk_mul_f32 v[68:69], v[68:69], v[152:153] op_sel:[0,1] op_sel_hi:[1,1]
	v_pk_mul_f32 v[58:59], v[58:59], v[152:153] op_sel:[0,1] op_sel_hi:[1,1]
	v_pk_mul_f32 v[60:61], v[60:61], v[152:153] op_sel:[0,1] op_sel_hi:[1,1]
	v_pk_mul_f32 v[66:67], v[66:67], v[70:71]
	v_pk_mul_f32 v[68:69], v[68:69], v[72:73]
	v_pk_mul_f32 v[58:59], v[58:59], v[62:63]
	v_pk_mul_f32 v[60:61], v[60:61], v[64:65]
	v_cvt_pk_bf16_f32 v62, v66, v67
	v_cvt_pk_bf16_f32 v63, v68, v69
	v_cvt_pk_bf16_f32 v64, v58, v59
	v_cvt_pk_bf16_f32 v65, v60, v61
	s_mov_b64 s[30:31], 0x6e000
	v_lshl_add_u64 v[136:137], v[136:137], 0, s[30:31]
	global_store_dwordx4 v[136:137], v[62:65], off
	s_waitcnt lgkmcnt(2)
; #define LAS __attribute__((address_space(3)))
; __device__ __forceinline__ u32x4 pack8(const f32x4 a, const f32x4 b) { u32x4 w; w.x = cvtpk(a[0], a[1]); w.y = cvtpk(a[2], a[3]); w.z = cvtpk(b[0], b[1]); w.w = cvtpk(b[2], b[3]); return w; }
; __device__ __forceinline__ void rs_commit(LAS unsigned char* lds, const PrepRegs& r, int ui, int tid) {
;     const f32x4 s4 = r.a + r.b; float s = (s4[0] + s4[1]) + (s4[2] + s4[3]); s += __shfl_xor(s, 1);
;     if ((tid & 1) == 0) ((LAS float*)(lds + LDS_RSTAB))[(ui & 1) * 256 + (tid >> 1)] = rsqrtf(s * (1.0f / DM) + EPS);
; }
;     __device__ __forceinline__ void run(const f32x4 (&acc)[2][2][4][2], const Unit& u, int wr, int wc, int fr, int fq, const int nai, LAS unsigned char* lds, const int ui) const {
;     ...
;         for (int ai = 0; ai < nai; ++ai)
; #pragma unroll
;             for (int m = 0; m < 4; ++m) {
;                 const int r = u.pm * 256 + ai * 128 + wr * 64 + m * 16 + fr;
;                 const float rs = RT[ai * 128 + wr * 64 + m * 16 + fr];
;                 f32x4 a[2];
; #pragma unroll
;                 for (int n = 0; n < 2; ++n) {
;                     const f32x4 g = acc[ai][0][m][n] * rs, uu = acc[ai][1][m][n] * rs;
; #pragma unroll
;                     for (int i = 0; i < 4; ++i) a[n][i] = g[i] * uu[i] * __builtin_amdgcn_rcpf(1.0f + __expf(-g[i]));
;                 }
;                 *(u32x4*)(ACT + (size_t)r * DFF + u.pn * 128 + wc * 32 + 8 * fq) = pack8(a[0], a[1]);
	v_mul_f32_e32 v152, 0xbfb8aa3b, v130
	v_mul_f32_e32 v153, v130, v130
	v_pk_mul_f32 v[42:43], v[46:47], v[42:43]
	v_pk_mul_f32 v[44:45], v[48:49], v[44:45]
	v_pk_mul_f32 v[34:35], v[38:39], v[34:35]
	v_pk_mul_f32 v[36:37], v[40:41], v[36:37]
	v_pk_mul_f32 v[46:47], v[46:47], v[152:153] op_sel_hi:[1,0]
	v_pk_mul_f32 v[48:49], v[48:49], v[152:153] op_sel_hi:[1,0]
	v_pk_mul_f32 v[38:39], v[38:39], v[152:153] op_sel_hi:[1,0]
	v_pk_mul_f32 v[40:41], v[40:41], v[152:153] op_sel_hi:[1,0]
	v_exp_f32_e32 v46, v46
	v_exp_f32_e32 v47, v47
	v_exp_f32_e32 v48, v48
	v_exp_f32_e32 v49, v49
	v_exp_f32_e32 v38, v38
	v_exp_f32_e32 v39, v39
	v_exp_f32_e32 v40, v40
	v_exp_f32_e32 v41, v41
	v_pk_add_f32 v[46:47], v[46:47], 1.0 op_sel_hi:[1,0]
	v_pk_add_f32 v[48:49], v[48:49], 1.0 op_sel_hi:[1,0]
	v_pk_add_f32 v[38:39], v[38:39], 1.0 op_sel_hi:[1,0]
	v_pk_add_f32 v[40:41], v[40:41], 1.0 op_sel_hi:[1,0]
	v_rcp_f32_e32 v46, v46
	v_rcp_f32_e32 v47, v47
	v_rcp_f32_e32 v48, v48
	v_rcp_f32_e32 v49, v49
	v_rcp_f32_e32 v38, v38
	v_rcp_f32_e32 v39, v39
	v_rcp_f32_e32 v40, v40
	v_rcp_f32_e32 v41, v41
	v_pk_mul_f32 v[42:43], v[42:43], v[152:153] op_sel:[0,1] op_sel_hi:[1,1]
	v_pk_mul_f32 v[44:45], v[44:45], v[152:153] op_sel:[0,1] op_sel_hi:[1,1]
	v_pk_mul_f32 v[34:35], v[34:35], v[152:153] op_sel:[0,1] op_sel_hi:[1,1]
	v_pk_mul_f32 v[36:37], v[36:37], v[152:153] op_sel:[0,1] op_sel_hi:[1,1]
	v_pk_mul_f32 v[42:43], v[42:43], v[46:47]
	v_pk_mul_f32 v[44:45], v[44:45], v[48:49]
	v_pk_mul_f32 v[34:35], v[34:35], v[38:39]
	v_pk_mul_f32 v[36:37], v[36:37], v[40:41]
	v_cvt_pk_bf16_f32 v38, v42, v43
	v_cvt_pk_bf16_f32 v39, v44, v45
	v_cvt_pk_bf16_f32 v40, v34, v35
	v_cvt_pk_bf16_f32 v41, v36, v37
	s_mov_b64 s[30:31], 0x16000
	v_lshl_add_u64 v[136:137], v[136:137], 0, s[30:31]
	global_store_dwordx4 v[136:137], v[38:41], off
	s_waitcnt lgkmcnt(1)
	v_mul_f32_e32 v152, 0xbfb8aa3b, v131
	v_mul_f32_e32 v153, v131, v131
	v_pk_mul_f32 v[26:27], v[30:31], v[26:27]
	v_pk_mul_f32 v[28:29], v[32:33], v[28:29]
	v_pk_mul_f32 v[18:19], v[22:23], v[18:19]
	v_pk_mul_f32 v[20:21], v[24:25], v[20:21]
	v_pk_mul_f32 v[30:31], v[30:31], v[152:153] op_sel_hi:[1,0]
	v_pk_mul_f32 v[32:33], v[32:33], v[152:153] op_sel_hi:[1,0]
	v_pk_mul_f32 v[22:23], v[22:23], v[152:153] op_sel_hi:[1,0]
	v_pk_mul_f32 v[24:25], v[24:25], v[152:153] op_sel_hi:[1,0]
	v_exp_f32_e32 v30, v30
	v_exp_f32_e32 v31, v31
	v_exp_f32_e32 v32, v32
	v_exp_f32_e32 v33, v33
	v_exp_f32_e32 v22, v22
	v_exp_f32_e32 v23, v23
	v_exp_f32_e32 v24, v24
	v_exp_f32_e32 v25, v25
	v_pk_add_f32 v[30:31], v[30:31], 1.0 op_sel_hi:[1,0]
	v_pk_add_f32 v[32:33], v[32:33], 1.0 op_sel_hi:[1,0]
	v_pk_add_f32 v[22:23], v[22:23], 1.0 op_sel_hi:[1,0]
	v_pk_add_f32 v[24:25], v[24:25], 1.0 op_sel_hi:[1,0]
	v_rcp_f32_e32 v30, v30
	v_rcp_f32_e32 v31, v31
	v_rcp_f32_e32 v32, v32
	v_rcp_f32_e32 v33, v33
	v_rcp_f32_e32 v22, v22
	v_rcp_f32_e32 v23, v23
	v_rcp_f32_e32 v24, v24
	v_rcp_f32_e32 v25, v25
	v_pk_mul_f32 v[26:27], v[26:27], v[152:153] op_sel:[0,1] op_sel_hi:[1,1]
	v_pk_mul_f32 v[28:29], v[28:29], v[152:153] op_sel:[0,1] op_sel_hi:[1,1]
	v_pk_mul_f32 v[18:19], v[18:19], v[152:153] op_sel:[0,1] op_sel_hi:[1,1]
	v_pk_mul_f32 v[20:21], v[20:21], v[152:153] op_sel:[0,1] op_sel_hi:[1,1]
	v_pk_mul_f32 v[26:27], v[26:27], v[30:31]
	v_pk_mul_f32 v[28:29], v[28:29], v[32:33]
	v_pk_mul_f32 v[18:19], v[18:19], v[22:23]
	v_pk_mul_f32 v[20:21], v[20:21], v[24:25]
	v_cvt_pk_bf16_f32 v22, v26, v27
	v_cvt_pk_bf16_f32 v23, v28, v29
	v_cvt_pk_bf16_f32 v24, v18, v19
	v_cvt_pk_bf16_f32 v25, v20, v21
	s_mov_b64 s[30:31], 0x16000
	v_lshl_add_u64 v[136:137], v[136:137], 0, s[30:31]
	global_store_dwordx4 v[136:137], v[22:25], off
	s_waitcnt lgkmcnt(0)
	v_mul_f32_e32 v152, 0xbfb8aa3b, v132
	v_mul_f32_e32 v153, v132, v132
	v_pk_mul_f32 v[10:11], v[14:15], v[10:11]
	v_pk_mul_f32 v[12:13], v[16:17], v[12:13]
	v_pk_mul_f32 v[2:3], v[6:7], v[2:3]
	v_pk_mul_f32 v[4:5], v[8:9], v[4:5]
	v_pk_mul_f32 v[14:15], v[14:15], v[152:153] op_sel_hi:[1,0]
	v_pk_mul_f32 v[16:17], v[16:17], v[152:153] op_sel_hi:[1,0]
	v_pk_mul_f32 v[6:7], v[6:7], v[152:153] op_sel_hi:[1,0]
	v_pk_mul_f32 v[8:9], v[8:9], v[152:153] op_sel_hi:[1,0]
	v_exp_f32_e32 v14, v14
	v_exp_f32_e32 v15, v15
	v_exp_f32_e32 v16, v16
	v_exp_f32_e32 v17, v17
	v_exp_f32_e32 v6, v6
	v_exp_f32_e32 v7, v7
	v_exp_f32_e32 v8, v8
	v_exp_f32_e32 v9, v9
	v_pk_add_f32 v[14:15], v[14:15], 1.0 op_sel_hi:[1,0]
	v_pk_add_f32 v[16:17], v[16:17], 1.0 op_sel_hi:[1,0]
	v_pk_add_f32 v[6:7], v[6:7], 1.0 op_sel_hi:[1,0]
	v_pk_add_f32 v[8:9], v[8:9], 1.0 op_sel_hi:[1,0]
	v_rcp_f32_e32 v14, v14
	v_rcp_f32_e32 v15, v15
	v_rcp_f32_e32 v16, v16
	v_rcp_f32_e32 v17, v17
	v_rcp_f32_e32 v6, v6
	v_rcp_f32_e32 v7, v7
	v_rcp_f32_e32 v8, v8
	v_rcp_f32_e32 v9, v9
	v_pk_mul_f32 v[10:11], v[10:11], v[152:153] op_sel:[0,1] op_sel_hi:[1,1]
	v_pk_mul_f32 v[12:13], v[12:13], v[152:153] op_sel:[0,1] op_sel_hi:[1,1]
	v_pk_mul_f32 v[2:3], v[2:3], v[152:153] op_sel:[0,1] op_sel_hi:[1,1]
	v_pk_mul_f32 v[4:5], v[4:5], v[152:153] op_sel:[0,1] op_sel_hi:[1,1]
	v_pk_mul_f32 v[10:11], v[10:11], v[14:15]
	v_pk_mul_f32 v[12:13], v[12:13], v[16:17]
	v_pk_mul_f32 v[2:3], v[2:3], v[6:7]
	v_pk_mul_f32 v[4:5], v[4:5], v[8:9]
	v_cvt_pk_bf16_f32 v6, v10, v11
	v_cvt_pk_bf16_f32 v7, v12, v13
	v_cvt_pk_bf16_f32 v8, v2, v3
	v_cvt_pk_bf16_f32 v9, v4, v5
	s_mov_b64 s[30:31], 0x16000
	v_lshl_add_u64 v[136:137], v[136:137], 0, s[30:31]
	global_store_dwordx4 v[136:137], v[6:9], off
	s_waitcnt vmcnt(0)
	s_nop 0
	v_pk_add_f32 v[2:3], v[52:53], v[56:57]
	v_pk_add_f32 v[4:5], v[50:51], v[54:55]
	v_add_f32_e32 v2, v2, v3
	v_add_f32_e32 v4, v4, v5
	v_add_f32_e32 v2, v4, v2
	ds_bpermute_b32 v3, v155, v2
	s_and_saveexec_b64 s[46:47], s[40:41]
	s_cbranch_execz .LBB0_786
	s_waitcnt lgkmcnt(0)
	v_add_f32_e32 v2, v2, v3
	v_fmamk_f32 v2, v2, 0x3a800000, v214
	s_mov_b32 s11, 0x800000
	v_cmp_gt_f32_e32 vcc, s11, v2
	v_mul_f32_e32 v3, 0x4b800000, v2
	s_lshl_b32 s11, s27, 10
	v_cndmask_b32_e32 v2, v2, v3, vcc
	v_rsq_f32_e32 v2, v2
	s_and_b32 s11, s11, 0x400
	v_mul_f32_e32 v3, 0x45800000, v2
	v_cndmask_b32_e32 v2, v2, v3, vcc
	v_add_u32_e32 v3, s11, v159
	ds_write_b32 v3, v2
